# v10 + s_setprio 1 for waves 4-7 during their QK MFMA run
# baseline (speedup 1.0000x reference)
.LBB0_717:
	s_add_i32 s6, s60, 6
	s_cmp_lt_u32 s6, s55
	s_cselect_b32 s6, s6, s58
	s_mul_i32 s63, s61, 0xa000
	s_lshl_b32 s6, s6, 6
	s_add_i32 s63, s63, 0
	s_add_i32 s75, s63, s30
	s_lshl_b64 s[64:65], s[6:7], 12
	s_add_u32 s66, s10, s64
	s_addc_u32 s67, s11, s65
	s_add_u32 s64, s12, s64
	v_lshl_add_u64 v[2:3], s[66:67], 0, v[172:173]
	s_mov_b32 m0, s75
	s_addc_u32 s65, s13, s65
	global_load_lds_dwordx4 v[2:3], off
	v_lshl_add_u64 v[2:3], s[66:67], 0, v[170:171]
	s_add_i32 m0, s75, 0x400
	s_lshl_b64 s[66:67], s[6:7], 7
	s_add_i32 s6, s63, s34
	global_load_lds_dwordx4 v[2:3], off
	v_lshl_add_u64 v[2:3], v[178:179], 0, s[66:67]
	s_add_i32 m0, s6, 0x4000
	s_nop 0
	global_load_lds_dwordx4 v[2:3], off
	v_lshl_add_u64 v[2:3], s[64:65], 0, v[168:169]
	s_add_i32 m0, s75, 0x6000
	s_nop 0
	global_load_lds_dwordx4 v[2:3], off
	v_lshl_add_u64 v[2:3], s[64:65], 0, v[166:167]
	s_add_i32 m0, s75, 0x6400
	s_nop 0
	global_load_lds_dwordx4 v[2:3], off
	s_sub_i32 s6, s53, 63
	s_cmp_le_u32 s6, s59
	s_cselect_b64 s[18:19], -1, 0
	s_cmp_gt_u32 s6, s59
	s_mul_i32 s62, s54, 0xa000
	s_cbranch_scc1 .LBB0_719
	v_add_u32_e32 v1, s62, v195
	v_add_u32_e32 v13, s62, v204
	v_add_u32_e32 v14, v1, v196
	ds_read_b128 v[2:5], v14
	ds_read_b128 v[6:9], v14 offset:8192
	v_add_u32_e32 v15, v1, v197
	ds_read_b128 v[220:223], v15
	ds_read_b128 v[224:227], v15 offset:8192
	v_add_u32_e32 v14, v1, v198
	ds_read_b128 v[228:231], v14
	ds_read_b128 v[232:235], v14 offset:8192
	s_cmp_lt_u32 s33, 4
	s_cbranch_scc1 .Lpr_m4
	s_setprio 1
.Lpr_m4:
	s_waitcnt lgkmcnt(4)
	v_mfma_f32_32x32x16_bf16 v[16:31], v[2:5], v[112:115], 0
	v_mfma_f32_32x32x16_bf16 v[32:47], v[6:9], v[112:115], 0
	v_add_u32_e32 v15, v1, v199
	ds_read_b128 v[236:239], v15
	ds_read_b128 v[240:243], v15 offset:8192
	s_waitcnt lgkmcnt(4)
	v_mfma_f32_32x32x16_bf16 v[16:31], v[220:223], v[116:119], v[16:31]
	v_mfma_f32_32x32x16_bf16 v[32:47], v[224:227], v[116:119], v[32:47]
	v_add_u32_e32 v14, v1, v200
	ds_read_b128 v[2:5], v14
	ds_read_b128 v[6:9], v14 offset:8192
	s_waitcnt lgkmcnt(4)
	v_mfma_f32_32x32x16_bf16 v[16:31], v[228:231], v[120:123], v[16:31]
	v_mfma_f32_32x32x16_bf16 v[32:47], v[232:235], v[120:123], v[32:47]
	v_add_u32_e32 v15, v1, v201
	ds_read_b128 v[220:223], v15
	ds_read_b128 v[224:227], v15 offset:8192
	s_waitcnt lgkmcnt(4)
	v_mfma_f32_32x32x16_bf16 v[16:31], v[236:239], v[124:127], v[16:31]
	v_mfma_f32_32x32x16_bf16 v[32:47], v[240:243], v[124:127], v[32:47]
	v_add_u32_e32 v14, v1, v202
	ds_read_b128 v[228:231], v14
	ds_read_b128 v[232:235], v14 offset:8192
	s_waitcnt lgkmcnt(4)
	v_mfma_f32_32x32x16_bf16 v[16:31], v[2:5], v[128:131], v[16:31]
	v_mfma_f32_32x32x16_bf16 v[32:47], v[6:9], v[128:131], v[32:47]
	v_add_u32_e32 v15, v1, v203
	ds_read_b128 v[236:239], v15
	ds_read_b128 v[240:243], v15 offset:8192
	s_waitcnt lgkmcnt(4)
	v_mfma_f32_32x32x16_bf16 v[16:31], v[220:223], v[132:135], v[16:31]
	v_mfma_f32_32x32x16_bf16 v[32:47], v[224:227], v[132:135], v[32:47]
	v_add_u32_e32 v14, v13, v205
	ds_read_b128 v[2:5], v14 offset:16384
	ds_read_b128 v[6:9], v14 offset:20480
	s_waitcnt lgkmcnt(4)
	v_mfma_f32_32x32x16_bf16 v[16:31], v[228:231], v[136:139], v[16:31]
	v_mfma_f32_32x32x16_bf16 v[32:47], v[232:235], v[136:139], v[32:47]
	v_add_u32_e32 v15, v13, v206
	ds_read_b128 v[220:223], v15 offset:16384
	ds_read_b128 v[224:227], v15 offset:20480
	s_waitcnt lgkmcnt(4)
	v_mfma_f32_32x32x16_bf16 v[16:31], v[236:239], v[140:143], v[16:31]
	v_mfma_f32_32x32x16_bf16 v[32:47], v[240:243], v[140:143], v[32:47]
	v_add_u32_e32 v14, v13, v207
	ds_read_b128 v[228:231], v14 offset:16384
	ds_read_b128 v[232:235], v14 offset:20480
	s_waitcnt lgkmcnt(4)
	v_mfma_f32_32x32x16_bf16 v[16:31], v[2:5], v[144:147], v[16:31]
	v_mfma_f32_32x32x16_bf16 v[32:47], v[6:9], v[144:147], v[32:47]
	v_add_u32_e32 v15, v13, v208
	ds_read_b128 v[236:239], v15 offset:16384
	ds_read_b128 v[240:243], v15 offset:20480
	s_waitcnt lgkmcnt(4)
	v_mfma_f32_32x32x16_bf16 v[16:31], v[220:223], v[148:151], v[16:31]
	v_mfma_f32_32x32x16_bf16 v[32:47], v[224:227], v[148:151], v[32:47]
	s_waitcnt lgkmcnt(2)
	v_mfma_f32_32x32x16_bf16 v[16:31], v[228:231], v[152:155], v[16:31]
	v_mfma_f32_32x32x16_bf16 v[32:47], v[232:235], v[152:155], v[32:47]
	s_waitcnt lgkmcnt(0)
	v_mfma_f32_32x32x16_bf16 v[16:31], v[236:239], v[156:159], v[16:31]
	v_mfma_f32_32x32x16_bf16 v[32:47], v[240:243], v[156:159], v[32:47]
	s_cmp_lt_u32 s33, 4
	s_cbranch_scc1 .Lpr_m3
	s_setprio 0
.Lpr_m3:
.LBB0_719:
	s_andn2_b64 vcc, exec, s[18:19]
	s_cbranch_vccnz .LBB0_716
	s_cmp_le_u32 s53, s59
	s_cbranch_scc1 .LBB0_722
	v_cmp_gt_u32_e32 vcc, 2.0, v216
	v_add_u32_e32 v1, 0xbfffffe0, v216
	s_nop 0
	v_cndmask_b32_e32 v16, v215, v16, vcc
	v_cmp_lt_u32_e32 vcc, s39, v1
	v_add_u32_e32 v1, 0xbfffffff, v216
	s_nop 0
	v_cndmask_b32_e32 v32, v215, v32, vcc
	v_cmp_lt_u32_e32 vcc, s39, v1
	v_add_u32_e32 v1, 0xbfffffdf, v216
	s_nop 0
	v_cndmask_b32_e32 v17, v215, v17, vcc
	v_cmp_lt_u32_e32 vcc, s39, v1
	v_add_u32_e32 v1, 0xbffffffe, v216
	s_nop 0
	v_cndmask_b32_e32 v33, v215, v33, vcc
	v_cmp_lt_u32_e32 vcc, s39, v1
	v_add_u32_e32 v1, 0xbfffffde, v216
	s_nop 0
	v_cndmask_b32_e32 v18, v215, v18, vcc
	v_cmp_lt_u32_e32 vcc, s39, v1
	v_add_u32_e32 v1, 0xbffffffd, v216
	s_nop 0
	v_cndmask_b32_e32 v34, v215, v34, vcc
	v_cmp_lt_u32_e32 vcc, s39, v1
	v_add_u32_e32 v1, 0xbfffffdd, v216
	s_nop 0
	v_cndmask_b32_e32 v19, v215, v19, vcc
	v_cmp_lt_u32_e32 vcc, s39, v1
	v_add_u32_e32 v1, 0xbffffff8, v216
	s_nop 0
	v_cndmask_b32_e32 v35, v215, v35, vcc
	v_cmp_lt_u32_e32 vcc, s39, v1
	v_add_u32_e32 v1, 0xbfffffd8, v216
	s_nop 0
	v_cndmask_b32_e32 v20, v215, v20, vcc
	v_cmp_lt_u32_e32 vcc, s39, v1
	v_add_u32_e32 v1, 0xbffffff7, v216
	s_nop 0
	v_cndmask_b32_e32 v36, v215, v36, vcc
	v_cmp_lt_u32_e32 vcc, s39, v1
	v_add_u32_e32 v1, 0xbfffffd7, v216
	s_nop 0
	v_cndmask_b32_e32 v21, v215, v21, vcc
	v_cmp_lt_u32_e32 vcc, s39, v1
	v_add_u32_e32 v1, 0xbffffff6, v216
	s_nop 0
	v_cndmask_b32_e32 v37, v215, v37, vcc
	v_cmp_lt_u32_e32 vcc, s39, v1
	v_add_u32_e32 v1, 0xbfffffd6, v216
	s_nop 0
	v_cndmask_b32_e32 v22, v215, v22, vcc
	v_cmp_lt_u32_e32 vcc, s39, v1
	v_add_u32_e32 v1, 0xbffffff5, v216
	s_nop 0
	v_cndmask_b32_e32 v38, v215, v38, vcc
	v_cmp_lt_u32_e32 vcc, s39, v1
	v_add_u32_e32 v1, 0xbfffffd5, v216
	s_nop 0
	v_cndmask_b32_e32 v23, v215, v23, vcc
	v_cmp_lt_u32_e32 vcc, s39, v1
	v_add_u32_e32 v1, 0xbffffff0, v216
	s_nop 0
	v_cndmask_b32_e32 v39, v215, v39, vcc
	v_cmp_lt_u32_e32 vcc, s39, v1
	v_add_u32_e32 v1, 0xbfffffd0, v216
	s_nop 0
	v_cndmask_b32_e32 v24, v215, v24, vcc
	v_cmp_lt_u32_e32 vcc, s39, v1
	v_add_u32_e32 v1, 0xbfffffef, v216
	s_nop 0
	v_cndmask_b32_e32 v40, v215, v40, vcc
	v_cmp_lt_u32_e32 vcc, s39, v1
	v_add_u32_e32 v1, 0xbfffffcf, v216
	s_nop 0
	v_cndmask_b32_e32 v25, v215, v25, vcc
	v_cmp_lt_u32_e32 vcc, s39, v1
	v_add_u32_e32 v1, 0xbfffffee, v216
	s_nop 0
	v_cndmask_b32_e32 v41, v215, v41, vcc
	v_cmp_lt_u32_e32 vcc, s39, v1
	v_add_u32_e32 v1, 0xbfffffce, v216
	s_nop 0
	v_cndmask_b32_e32 v26, v215, v26, vcc
	v_cmp_lt_u32_e32 vcc, s39, v1
	v_add_u32_e32 v1, 0xbfffffed, v216
	s_nop 0
	v_cndmask_b32_e32 v42, v215, v42, vcc
	v_cmp_lt_u32_e32 vcc, s39, v1
	v_add_u32_e32 v1, 0xbfffffcd, v216
	s_nop 0
	v_cndmask_b32_e32 v27, v215, v27, vcc
	v_cmp_lt_u32_e32 vcc, s39, v1
	v_add_u32_e32 v1, 0xbfffffe8, v216
	s_nop 0
	v_cndmask_b32_e32 v43, v215, v43, vcc
	v_cmp_lt_u32_e32 vcc, s39, v1
	v_add_u32_e32 v1, 0xbfffffc8, v216
	s_nop 0
	v_cndmask_b32_e32 v28, v215, v28, vcc
	v_cmp_lt_u32_e32 vcc, s39, v1
	v_add_u32_e32 v1, 0xbfffffe7, v216
	s_nop 0
	v_cndmask_b32_e32 v44, v215, v44, vcc
	v_cmp_lt_u32_e32 vcc, s39, v1
	v_add_u32_e32 v1, 0xbfffffc7, v216
	s_nop 0
	v_cndmask_b32_e32 v29, v215, v29, vcc
	v_cmp_lt_u32_e32 vcc, s39, v1
	v_add_u32_e32 v1, 0xbfffffe6, v216
	s_nop 0
	v_cndmask_b32_e32 v45, v215, v45, vcc
	v_cmp_lt_u32_e32 vcc, s39, v1
	v_add_u32_e32 v1, 0xbfffffc6, v216
	s_nop 0
	v_cndmask_b32_e32 v30, v215, v30, vcc
	v_cmp_lt_u32_e32 vcc, s39, v1
	v_add_u32_e32 v1, 0xbfffffe5, v216
	s_nop 0
	v_cndmask_b32_e32 v46, v215, v46, vcc
	v_cmp_lt_u32_e32 vcc, s39, v1
	v_add_u32_e32 v1, 0xbfffffc5, v216
	s_nop 0
	v_cndmask_b32_e32 v31, v215, v31, vcc
	v_cmp_lt_u32_e32 vcc, s39, v1
	s_nop 1
	v_cndmask_b32_e32 v47, v215, v47, vcc

.LBB0_1511:
	s_add_i32 s26, s81, 6
	s_cmp_lt_u32 s26, s79
	s_cselect_b32 s26, s26, s85
	s_lshl_b32 s26, s26, 6
	s_lshl_b32 s87, s82, 15
	s_add_i32 s87, s50, s87
	s_lshl_b64 s[88:89], s[26:27], 12
	s_add_u32 s90, s30, s88
	s_addc_u32 s91, s31, s89
	s_add_u32 s88, s34, s88
	v_lshl_add_u64 v[2:3], s[90:91], 0, v[154:155]
	s_mov_b32 m0, s87
	s_addc_u32 s89, s35, s89
	global_load_lds_dwordx4 v[2:3], off
	v_lshl_add_u64 v[2:3], s[90:91], 0, v[152:153]
	s_add_i32 m0, s87, 0x400
	s_nop 0
	global_load_lds_dwordx4 v[2:3], off
	v_lshl_add_u64 v[2:3], s[88:89], 0, v[150:151]
	s_add_i32 m0, s87, 0x4000
	s_nop 0
	global_load_lds_dwordx4 v[2:3], off
	v_lshl_add_u64 v[2:3], s[88:89], 0, v[148:149]
	s_add_i32 m0, s87, 0x4400
	s_nop 0
	global_load_lds_dwordx4 v[2:3], off
	s_sub_i32 s26, s83, 63
	s_cmp_le_u32 s26, s86
	s_cselect_b64 s[38:39], -1, 0
	s_cmp_gt_u32 s26, s86
	s_cbranch_scc1 .LBB0_1513
	v_lshl_add_u32 v1, s80, 15, v178
	ds_read_b128 v[16:19], v203
	ds_read_b128 v[20:23], v203 offset:32
	ds_read_b128 v[24:27], v203 offset:64
	ds_read_b128 v[28:31], v203 offset:96
	ds_read_b128 v[32:35], v203 offset:128
	ds_read_b128 v[36:39], v203 offset:160
	ds_read_b128 v[40:43], v203 offset:192
	ds_read_b128 v[44:47], v203 offset:224
	v_add_u32_e32 v14, v1, v179
	ds_read_b128 v[2:5], v14
	ds_read_b128 v[6:9], v14 offset:8192
	v_add_u32_e32 v15, v1, v180
	ds_read_b128 v[208:211], v15
	ds_read_b128 v[212:215], v15 offset:8192
	v_add_u32_e32 v14, v1, v181
	ds_read_b128 v[216:219], v14
	ds_read_b128 v[220:223], v14 offset:8192
	s_cmp_lt_u32 s33, 4
	s_cbranch_scc1 .Lpr_f2
	s_setprio 1
.Lpr_f2:
	s_waitcnt lgkmcnt(4)
	v_mfma_f32_32x32x16_bf16 v[16:31], v[2:5], v[112:115], v[16:31]
	v_mfma_f32_32x32x16_bf16 v[32:47], v[6:9], v[112:115], v[32:47]
	v_add_u32_e32 v15, v1, v182
	ds_read_b128 v[224:227], v15
	ds_read_b128 v[228:231], v15 offset:8192
	s_waitcnt lgkmcnt(4)
	v_mfma_f32_32x32x16_bf16 v[16:31], v[208:211], v[116:119], v[16:31]
	v_mfma_f32_32x32x16_bf16 v[32:47], v[212:215], v[116:119], v[32:47]
	v_add_u32_e32 v14, v1, v183
	ds_read_b128 v[2:5], v14
	ds_read_b128 v[6:9], v14 offset:8192
	s_waitcnt lgkmcnt(4)
	v_mfma_f32_32x32x16_bf16 v[16:31], v[216:219], v[120:123], v[16:31]
	v_mfma_f32_32x32x16_bf16 v[32:47], v[220:223], v[120:123], v[32:47]
	v_add_u32_e32 v15, v1, v184
	ds_read_b128 v[208:211], v15
	ds_read_b128 v[212:215], v15 offset:8192
	s_waitcnt lgkmcnt(4)
	v_mfma_f32_32x32x16_bf16 v[16:31], v[224:227], v[124:127], v[16:31]
	v_mfma_f32_32x32x16_bf16 v[32:47], v[228:231], v[124:127], v[32:47]
	v_add_u32_e32 v14, v1, v185
	ds_read_b128 v[216:219], v14
	ds_read_b128 v[220:223], v14 offset:8192
	s_waitcnt lgkmcnt(4)
	v_mfma_f32_32x32x16_bf16 v[16:31], v[2:5], v[128:131], v[16:31]
	v_mfma_f32_32x32x16_bf16 v[32:47], v[6:9], v[128:131], v[32:47]
	v_add_u32_e32 v15, v1, v186
	ds_read_b128 v[224:227], v15
	ds_read_b128 v[228:231], v15 offset:8192
	s_waitcnt lgkmcnt(4)
	v_mfma_f32_32x32x16_bf16 v[16:31], v[208:211], v[132:135], v[16:31]
	v_mfma_f32_32x32x16_bf16 v[32:47], v[212:215], v[132:135], v[32:47]
	s_waitcnt lgkmcnt(2)
	v_mfma_f32_32x32x16_bf16 v[16:31], v[216:219], v[136:139], v[16:31]
	v_mfma_f32_32x32x16_bf16 v[32:47], v[220:223], v[136:139], v[32:47]
	s_waitcnt lgkmcnt(0)
	v_mfma_f32_32x32x16_bf16 v[16:31], v[224:227], v[140:143], v[16:31]
	v_mfma_f32_32x32x16_bf16 v[32:47], v[228:231], v[140:143], v[32:47]
	s_cmp_lt_u32 s33, 4
	s_cbranch_scc1 .Lpr_f1
	s_setprio 0
.Lpr_f1:
.LBB0_1513:
	s_andn2_b64 vcc, exec, s[38:39]
	s_cbranch_vccnz .LBB0_1510
	s_cmp_le_u32 s83, s84
	s_cbranch_scc1 .LBB0_1516
	v_cmp_gt_u32_e32 vcc, 2.0, v201
	v_add_u32_e32 v1, 0xbfffffe0, v201
	s_nop 0
	v_cndmask_b32_e32 v16, v200, v16, vcc
	v_cmp_lt_u32_e32 vcc, s61, v1
	v_add_u32_e32 v1, 0xbfffffff, v201
	s_nop 0
	v_cndmask_b32_e32 v32, v200, v32, vcc
	v_cmp_lt_u32_e32 vcc, s61, v1
	v_add_u32_e32 v1, 0xbfffffdf, v201
	s_nop 0
	v_cndmask_b32_e32 v17, v200, v17, vcc
	v_cmp_lt_u32_e32 vcc, s61, v1
	v_add_u32_e32 v1, 0xbffffffe, v201
	s_nop 0
	v_cndmask_b32_e32 v33, v200, v33, vcc
	v_cmp_lt_u32_e32 vcc, s61, v1
	v_add_u32_e32 v1, 0xbfffffde, v201
	s_nop 0
	v_cndmask_b32_e32 v18, v200, v18, vcc
	v_cmp_lt_u32_e32 vcc, s61, v1
	v_add_u32_e32 v1, 0xbffffffd, v201
	s_nop 0
	v_cndmask_b32_e32 v34, v200, v34, vcc
	v_cmp_lt_u32_e32 vcc, s61, v1
	v_add_u32_e32 v1, 0xbfffffdd, v201
	s_nop 0
	v_cndmask_b32_e32 v19, v200, v19, vcc
	v_cmp_lt_u32_e32 vcc, s61, v1
	v_add_u32_e32 v1, 0xbffffff8, v201
	s_nop 0
	v_cndmask_b32_e32 v35, v200, v35, vcc
	v_cmp_lt_u32_e32 vcc, s61, v1
	v_add_u32_e32 v1, 0xbfffffd8, v201
	s_nop 0
	v_cndmask_b32_e32 v20, v200, v20, vcc
	v_cmp_lt_u32_e32 vcc, s61, v1
	v_add_u32_e32 v1, 0xbffffff7, v201
	s_nop 0
	v_cndmask_b32_e32 v36, v200, v36, vcc
	v_cmp_lt_u32_e32 vcc, s61, v1
	v_add_u32_e32 v1, 0xbfffffd7, v201
	s_nop 0
	v_cndmask_b32_e32 v21, v200, v21, vcc
	v_cmp_lt_u32_e32 vcc, s61, v1
	v_add_u32_e32 v1, 0xbffffff6, v201
	s_nop 0
	v_cndmask_b32_e32 v37, v200, v37, vcc
	v_cmp_lt_u32_e32 vcc, s61, v1
	v_add_u32_e32 v1, 0xbfffffd6, v201
	s_nop 0
	v_cndmask_b32_e32 v22, v200, v22, vcc
	v_cmp_lt_u32_e32 vcc, s61, v1
	v_add_u32_e32 v1, 0xbffffff5, v201
	s_nop 0
	v_cndmask_b32_e32 v38, v200, v38, vcc
	v_cmp_lt_u32_e32 vcc, s61, v1
	v_add_u32_e32 v1, 0xbfffffd5, v201
	s_nop 0
	v_cndmask_b32_e32 v23, v200, v23, vcc
	v_cmp_lt_u32_e32 vcc, s61, v1
	v_add_u32_e32 v1, 0xbffffff0, v201
	s_nop 0
	v_cndmask_b32_e32 v39, v200, v39, vcc
	v_cmp_lt_u32_e32 vcc, s61, v1
	v_add_u32_e32 v1, 0xbfffffd0, v201
	s_nop 0
	v_cndmask_b32_e32 v24, v200, v24, vcc
	v_cmp_lt_u32_e32 vcc, s61, v1
	v_add_u32_e32 v1, 0xbfffffef, v201
	s_nop 0
	v_cndmask_b32_e32 v40, v200, v40, vcc
	v_cmp_lt_u32_e32 vcc, s61, v1
	v_add_u32_e32 v1, 0xbfffffcf, v201
	s_nop 0
	v_cndmask_b32_e32 v25, v200, v25, vcc
	v_cmp_lt_u32_e32 vcc, s61, v1
	v_add_u32_e32 v1, 0xbfffffee, v201
	s_nop 0
	v_cndmask_b32_e32 v41, v200, v41, vcc
	v_cmp_lt_u32_e32 vcc, s61, v1
	v_add_u32_e32 v1, 0xbfffffce, v201
	s_nop 0
	v_cndmask_b32_e32 v26, v200, v26, vcc
	v_cmp_lt_u32_e32 vcc, s61, v1
	v_add_u32_e32 v1, 0xbfffffed, v201
	s_nop 0
	v_cndmask_b32_e32 v42, v200, v42, vcc
	v_cmp_lt_u32_e32 vcc, s61, v1
	v_add_u32_e32 v1, 0xbfffffcd, v201
	s_nop 0
	v_cndmask_b32_e32 v27, v200, v27, vcc
	v_cmp_lt_u32_e32 vcc, s61, v1
	v_add_u32_e32 v1, 0xbfffffe8, v201
	s_nop 0
	v_cndmask_b32_e32 v43, v200, v43, vcc
	v_cmp_lt_u32_e32 vcc, s61, v1
	v_add_u32_e32 v1, 0xbfffffc8, v201
	s_nop 0
	v_cndmask_b32_e32 v28, v200, v28, vcc
	v_cmp_lt_u32_e32 vcc, s61, v1
	v_add_u32_e32 v1, 0xbfffffe7, v201
	s_nop 0
	v_cndmask_b32_e32 v44, v200, v44, vcc
	v_cmp_lt_u32_e32 vcc, s61, v1
	v_add_u32_e32 v1, 0xbfffffc7, v201
	s_nop 0
	v_cndmask_b32_e32 v29, v200, v29, vcc
	v_cmp_lt_u32_e32 vcc, s61, v1
	v_add_u32_e32 v1, 0xbfffffe6, v201
	s_nop 0
	v_cndmask_b32_e32 v45, v200, v45, vcc
	v_cmp_lt_u32_e32 vcc, s61, v1
	v_add_u32_e32 v1, 0xbfffffc6, v201
	s_nop 0
	v_cndmask_b32_e32 v30, v200, v30, vcc
	v_cmp_lt_u32_e32 vcc, s61, v1
	v_add_u32_e32 v1, 0xbfffffe5, v201
	s_nop 0
	v_cndmask_b32_e32 v46, v200, v46, vcc
	v_cmp_lt_u32_e32 vcc, s61, v1
	v_add_u32_e32 v1, 0xbfffffc5, v201
	s_nop 0
	v_cndmask_b32_e32 v31, v200, v31, vcc
	v_cmp_lt_u32_e32 vcc, s61, v1
	s_nop 1
	v_cndmask_b32_e32 v47, v200, v47, vcc
